# selected-block attention: per-element bias and causal mask of the near blocks from a (distance, head) table in LDS built once per workgroup (16 LDS reads per step instead of the inline bucket arithmet
# speedup vs baseline: 1.0634x; 1.0530x over previous
.LBB0_841:
	s_andn2_b64 vcc, exec, s[0:1]
	v_readlane_b32 s3, v254, 47
	s_cbranch_vccnz .LBB0_934
	s_mov_b64 s[22:23], exec
	s_and_b32 s2, s3, 1
	s_lshr_b32 s0, s3, 1
	s_and_b32 s0, s0, 3
	s_lshl_b32 s26, s0, 12
	s_add_i32 s27, s26, 0x1000
	v_readfirstlane_b32 s1, v220
	s_and_b32 s0, s3, -8
	s_add_i32 s0, s0, s1
	s_add_i32 s26, s26, s0
	s_lshl_b32 s0, s2, 6
	s_add_u32 s12, s12, s0
	s_addc_u32 s13, s13, 0
	s_lshl_b32 s0, s2, 21
	s_add_u32 s18, s18, s0
	s_addc_u32 s19, s19, 0
	s_add_u32 s16, s16, s0
	s_addc_u32 s17, s17, 0
	v_lshl_or_b32 v202, s2, 3, v200
	s_lshl_b32 s63, s2, 3
	v_and_b32_e32 v140, 63, v208
	v_lshlrev_b32_e32 v140, 4, v140
	v_add_u32_e32 v141, 0x1000, v140
	s_mov_b32 s48, 0x3e38aa3b
	s_mov_b32 s49, 0x3e38aa3b
	s_mov_b32 s57, 0x20400
	v_mov_b32_e32 v179, 0xf149f2ca
	v_lshl_add_u32 v66, v202, 2, s57
	ds_read_b32 v178, v66 offset:1984
	s_barrier
	s_and_b32 s0, s1, 3
	s_lshl_b32 s0, s0, 11
	s_cmp_lt_u32 s1, 4
	s_cselect_b32 s40, s18, s16
	s_cselect_b32 s41, s19, s17
	s_cselect_b32 s2, 0, 0x2000
	s_add_u32 s40, s40, s0
	s_addc_u32 s41, s41, 0
	s_add_i32 s2, s2, s0
	s_mov_b32 m0, s2
	s_nop 0
	global_load_lds_dwordx4 v140, s[40:41]
	s_add_u32 s40, s40, 0x400
	s_addc_u32 s41, s41, 0
	s_add_i32 m0, s2, 0x400
	s_nop 0
	global_load_lds_dwordx4 v140, s[40:41]
	v_mov_b32_e32 v66, v208
	s_mov_b32 s0, 26
.Lsel_lut:
	v_lshrrev_b32_e32 v67, 3, v66
	v_add_u32_e32 v67, 0xffffffc0, v67
	v_and_b32_e32 v144, 7, v66
	v_max_i32_e32 v145, 0, v67
	v_cvt_f32_u32_e32 v143, v145
	v_mul_f32_e32 v143, 0x3d800000, v143
	v_log_f32_e32 v143, v143
	s_nop 0
	v_mul_f32_e32 v143, 0x40124925, v143
	v_cvt_i32_f32_e32 v143, v143
	v_med3_i32 v143, v143, 0, 15
	v_add_u32_e32 v143, 16, v143
	v_cmp_gt_u32_e32 vcc, 16, v145
	s_nop 1
	v_cndmask_b32_e32 v143, v143, v145, vcc
	v_lshl_add_u32 v143, v143, 4, v144
	v_add_u32_e32 v143, s63, v143
	v_lshl_add_u32 v143, v143, 2, s57
	ds_read_b32 v143, v143
	v_cmp_le_i32_e32 vcc, 0, v67
	s_waitcnt lgkmcnt(0)
	v_mul_f32_e32 v143, 0x3fb8aa3b, v143
	v_cndmask_b32_e32 v143, v179, v143, vcc
	v_lshlrev_b32_e32 v177, 2, v66
	v_add_u32_e32 v177, 0x4000, v177
	ds_write_b32 v177, v143
	v_add_u32_e32 v66, 0x200, v66
	s_add_i32 s0, s0, -1
	s_cmp_lg_u32 s0, 0
	s_cbranch_scc1 .Lsel_lut
	s_waitcnt lgkmcnt(0)
	s_waitcnt vmcnt(0)
	s_barrier
	s_lshl_b32 s0, s26, 7
	s_add_u32 s38, s12, s0
	s_addc_u32 s39, s13, 0
	v_lshrrev_b32_e32 v144, 3, v199
	global_load_dword v176, v144, s[38:39]
	s_lshl_b32 s0, s26, 11
	s_add_u32 s54, s14, s0
	s_addc_u32 s55, s15, 0
	v_lshlrev_b32_e32 v67, 7, v202
	v_lshl_add_u32 v67, v198, 1, v67
	global_load_dwordx4 v[16:19], v67, s[54:55]
	global_load_dwordx4 v[20:23], v67, s[54:55] offset:64
	s_mov_b64 s[34:35], s[18:19]
	s_mov_b64 s[36:37], s[16:17]
	ds_read_b128 v[32:35], v140 offset:0
	ds_read_b128 v[36:39], v140 offset:1024
	ds_read_b128 v[40:43], v140 offset:2048
	ds_read_b128 v[44:47], v140 offset:3072
	ds_read_b128 v[48:51], v140 offset:4096
	ds_read_b128 v[52:55], v140 offset:5120
	ds_read_b128 v[56:59], v140 offset:6144
	ds_read_b128 v[60:63], v140 offset:7168
	ds_read_b128 v[100:103], v140 offset:8192
	ds_read_b128 v[104:107], v140 offset:9216
	ds_read_b128 v[108:111], v140 offset:10240
	ds_read_b128 v[112:115], v140 offset:11264
	ds_read_b128 v[116:119], v140 offset:12288
	ds_read_b128 v[120:123], v140 offset:13312
	ds_read_b128 v[124:127], v140 offset:14336
	ds_read_b128 v[128:131], v140 offset:15360
	s_lshr_b32 s0, s26, 6
	s_add_i32 s0, s0, 1
	s_min_i32 s28, s0, 16
	s_mov_b32 s29, 0
	s_mov_b32 s30, 0
	s_mov_b32 s51, 0
	v_mov_b32_e32 v196, 0xf149f2ca
	v_mov_b32_e32 v197, 0
	v_mov_b32_e32 v0, 0
	v_mov_b32_e32 v1, 0
	v_mov_b32_e32 v2, 0
	v_mov_b32_e32 v3, 0
	v_mov_b32_e32 v4, 0
	v_mov_b32_e32 v5, 0
	v_mov_b32_e32 v6, 0
	v_mov_b32_e32 v7, 0
	v_mov_b32_e32 v8, 0
	v_mov_b32_e32 v9, 0
	v_mov_b32_e32 v10, 0
	v_mov_b32_e32 v11, 0
	v_mov_b32_e32 v12, 0
	v_mov_b32_e32 v13, 0
	v_mov_b32_e32 v14, 0
	v_mov_b32_e32 v15, 0
	s_waitcnt lgkmcnt(0)
	v_mul_f32_e32 v178, 0x3fb8aa3b, v178
	s_waitcnt vmcnt(2)

.Lsel_slow:
	s_add_i32 s1, s0, 13
	s_lshl_b32 s1, s1, 5
	s_add_i32 s1, s1, 0x4000
	v_lshlrev_b32_e32 v66, 5, v182
	v_sub_u32_e32 v66, s1, v66
	v_lshl_add_u32 v66, v200, 2, v66
	ds_read_b32 v222, v66 offset:1632
	ds_read_b32 v223, v66 offset:1600
	ds_read_b32 v224, v66 offset:1568
	ds_read_b32 v225, v66 offset:1536
	ds_read_b32 v226, v66 offset:1120
	ds_read_b32 v227, v66 offset:1088
	ds_read_b32 v228, v66 offset:1056
	ds_read_b32 v229, v66 offset:1024
	ds_read_b32 v230, v66 offset:608
	ds_read_b32 v231, v66 offset:576
	ds_read_b32 v232, v66 offset:544
	ds_read_b32 v233, v66 offset:512
	ds_read_b32 v234, v66 offset:96
	ds_read_b32 v235, v66 offset:64
	ds_read_b32 v236, v66 offset:32
	ds_read_b32 v237, v66 offset:0
	s_waitcnt lgkmcnt(0)
	v_pk_fma_f32 v[184:185], v[184:185], s[48:49], v[222:223] op_sel_hi:[1,0,1]
	v_pk_fma_f32 v[186:187], v[186:187], s[48:49], v[224:225] op_sel_hi:[1,0,1]
	v_pk_fma_f32 v[188:189], v[188:189], s[48:49], v[226:227] op_sel_hi:[1,0,1]
	v_pk_fma_f32 v[190:191], v[190:191], s[48:49], v[228:229] op_sel_hi:[1,0,1]
	v_pk_fma_f32 v[192:193], v[192:193], s[48:49], v[230:231] op_sel_hi:[1,0,1]
	v_pk_fma_f32 v[194:195], v[194:195], s[48:49], v[232:233] op_sel_hi:[1,0,1]
	v_pk_fma_f32 v[172:173], v[172:173], s[48:49], v[234:235] op_sel_hi:[1,0,1]
	v_pk_fma_f32 v[174:175], v[174:175], s[48:49], v[236:237] op_sel_hi:[1,0,1]
	s_cmp_eq_u32 s51, 0
	s_cbranch_scc1 .Lsel_maxA
	s_branch .Lsel_maxB
